# nt on ffnconv U loads (compiled phases 9/19)
# baseline (speedup 1.0000x reference)
.LBB0_1256:
	s_movk_i32 s4, 0x2bf
	v_cmp_lt_i32_e32 vcc, s4, v95
	v_add_lshl_u32 v48, v95, s24, 1
	s_and_saveexec_b64 s[4:5], vcc
	s_xor_b64 s[6:7], exec, s[4:5]
	s_cbranch_execz .LBB0_1271
	v_add_u32_e32 v2, 0xfffffa80, v48
	v_readlane_b32 s4, v232, 17
	v_lshlrev_b64 v[20:21], 2, v[2:3]
	v_readlane_b32 s5, v232, 18
	v_lshl_add_u64 v[22:23], s[14:15], 0, v[20:21]
	v_lshl_add_u64 v[24:25], s[26:27], 0, v[20:21]
	v_lshl_add_u64 v[8:9], s[4:5], 0, v[20:21]
	v_readlane_b32 s4, v232, 19
	v_add_co_u32_e32 v10, vcc, 0x5000, v8
	v_readlane_b32 s5, v232, 20
	s_nop 0
	v_addc_co_u32_e32 v11, vcc, 0, v9, vcc
	v_lshl_add_u64 v[12:13], s[4:5], 0, v[20:21]
	v_readlane_b32 s4, v232, 21
	v_add_co_u32_e32 v14, vcc, 0x5000, v12
	v_readlane_b32 s5, v232, 22
	s_nop 0
	v_addc_co_u32_e32 v15, vcc, 0, v13, vcc
	v_lshl_add_u64 v[16:17], s[4:5], 0, v[20:21]
	global_load_dwordx2 v[8:9], v[8:9], off
	s_nop 0
	global_load_dwordx2 v[10:11], v[10:11], off offset:2048
	s_nop 0
	global_load_dwordx2 v[12:13], v[12:13], off
	s_nop 0
	global_load_dwordx2 v[14:15], v[14:15], off offset:2048
	v_add_co_u32_e32 v18, vcc, 0x5000, v16
	v_readlane_b32 s4, v232, 25
	s_nop 0
	v_addc_co_u32_e32 v19, vcc, 0, v17, vcc
	global_load_dwordx2 v[16:17], v[16:17], off
	s_nop 0
	global_load_dwordx2 v[18:19], v[18:19], off offset:2048
	s_nop 0
	global_load_dwordx2 v[20:21], v[22:23], off
	s_nop 0
	global_load_dwordx2 v[22:23], v[24:25], off
	v_readlane_b32 s5, v232, 26
	s_andn2_b64 vcc, exec, s[4:5]
	v_lshl_add_u64 v[24:25], v[2:3], 1, s[10:11]
	s_cbranch_vccnz .LBB0_1259
	v_readlane_b32 s4, v232, 27
	v_readlane_b32 s5, v232, 28
	s_nop 1
	v_lshl_add_u64 v[26:27], v[24:25], 0, s[4:5]
	v_add_co_u32_e32 v28, vcc, 0x2000, v26
	s_nop 1
	v_addc_co_u32_e32 v29, vcc, 0, v27, vcc
	global_load_dword v30, v[26:27], off nt
	global_load_dword v31, v[28:29], off offset:3072 nt
	s_branch .LBB0_1260

.LBB0_1260:
	v_lshl_add_u64 v[26:27], v[24:25], 0, s[46:47]
	v_add_co_u32_e32 v28, vcc, 0x2000, v26
	v_lshl_add_u64 v[32:33], v[24:25], 0, s[44:45]
	s_nop 0
	v_addc_co_u32_e32 v29, vcc, 0, v27, vcc
	v_add_co_u32_e32 v34, vcc, 0x2000, v32
	v_lshl_add_u64 v[36:37], v[24:25], 0, s[48:49]
	s_nop 0
	v_addc_co_u32_e32 v35, vcc, 0, v33, vcc
	v_add_co_u32_e32 v42, vcc, 0x2000, v36
	s_waitcnt vmcnt(18)
	v_lshl_add_u64 v[46:47], v[24:25], 0, s[50:51]
	v_addc_co_u32_e32 v43, vcc, 0, v37, vcc
	v_add_co_u32_e32 v48, vcc, 0x2000, v46
	v_lshl_add_u64 v[52:53], v[24:25], 0, s[58:59]
	s_nop 0
	v_addc_co_u32_e32 v49, vcc, 0, v47, vcc
	global_load_dword v38, v[26:27], off nt
	global_load_dword v40, v[28:29], off offset:3072 nt
	global_load_dword v44, v[32:33], off nt
	global_load_dword v45, v[34:35], off offset:3072 nt
	s_nop 0
	global_load_dword v36, v[36:37], off nt
	s_nop 0
	global_load_dword v39, v[42:43], off offset:3072 nt
	global_load_dword v32, v[46:47], off nt
	global_load_dword v33, v[48:49], off offset:3072 nt
	v_lshl_add_u64 v[26:27], v[24:25], 0, s[52:53]
	v_add_co_u32_e32 v28, vcc, 0x2000, v26
	v_lshl_add_u64 v[34:35], v[24:25], 0, s[54:55]
	s_nop 0
	v_addc_co_u32_e32 v29, vcc, 0, v27, vcc
	v_add_co_u32_e32 v46, vcc, 0x2000, v34
	v_lshl_add_u64 v[48:49], v[24:25], 0, s[56:57]
	s_nop 0
	v_addc_co_u32_e32 v47, vcc, 0, v35, vcc
	v_add_co_u32_e32 v50, vcc, 0x2000, v48
	v_mov_b32_e32 v5, v3
	s_nop 0
	v_addc_co_u32_e32 v51, vcc, 0, v49, vcc
	v_add_co_u32_e32 v54, vcc, 0x2000, v52
	s_mov_b32 s4, 0
	s_nop 0
	v_addc_co_u32_e32 v55, vcc, 0, v53, vcc
	global_load_dword v43, v[26:27], off nt
	global_load_dword v42, v[28:29], off offset:3072 nt
	global_load_dword v37, v[34:35], off nt
	s_nop 0
	global_load_dword v34, v[46:47], off offset:3072 nt
	global_load_dword v35, v[48:49], off nt
	global_load_dword v41, v[50:51], off offset:3072 nt
	global_load_dword v2, v[52:53], off nt
	s_nop 0
	global_load_dword v47, v[54:55], off offset:3072 nt
	v_lshl_add_u64 v[26:27], v[24:25], 0, s[60:61]
	v_add_co_u32_e32 v28, vcc, 0x2000, v26
	v_lshl_add_u64 v[48:49], v[24:25], 0, s[62:63]
	s_nop 0
	v_addc_co_u32_e32 v29, vcc, 0, v27, vcc
	v_add_co_u32_e32 v50, vcc, 0x2000, v48
	v_lshl_add_u64 v[52:53], v[24:25], 0, s[64:65]
	s_nop 0
	v_addc_co_u32_e32 v51, vcc, 0, v49, vcc
	v_add_co_u32_e32 v54, vcc, 0x2000, v52
	s_mov_b64 s[8:9], s[92:93]
	s_nop 0
	v_addc_co_u32_e32 v55, vcc, 0, v53, vcc
	global_load_dword v57, v[26:27], off nt
	global_load_dword v61, v[28:29], off offset:3072 nt
	global_load_dword v65, v[48:49], off nt
	global_load_dword v66, v[50:51], off offset:3072 nt
	global_load_dword v63, v[54:55], off offset:3072 nt
	global_load_dword v67, v[52:53], off nt
	v_lshlrev_b64 v[26:27], 1, v[4:5]
	s_mov_b64 s[16:17], s[90:91]
	s_branch .LBB0_1262

.LBB0_1262:
	s_waitcnt vmcnt(6)
	v_mov_b32_e32 v51, v47
	s_waitcnt vmcnt(4)
	v_mov_b32_e32 v52, v61
	s_waitcnt vmcnt(2)
	v_mov_b32_e32 v53, v66
	s_waitcnt vmcnt(1)
	v_mov_b32_e32 v54, v63
	v_mov_b32_e32 v58, v2
	v_mov_b32_e32 v59, v57
	v_mov_b32_e32 v60, v65
	s_cmp_eq_u32 s4, 28
	s_waitcnt vmcnt(0)
	v_mov_b32_e32 v62, v67
	s_cbranch_scc1 .LBB0_1261
	v_lshl_add_u64 v[28:29], s[8:9], 0, v[26:27]
	v_add_co_u32_e32 v46, vcc, 0x15933000, v28
	s_add_i32 s5, s18, s4
	s_nop 0
	v_addc_co_u32_e32 v47, vcc, 0, v29, vcc
	v_add_co_u32_e32 v48, vcc, 0x15936000, v28
	s_add_i32 s5, s5, 5
	s_nop 0
	v_addc_co_u32_e32 v49, vcc, 0, v29, vcc
	global_load_dword v5, v[46:47], off offset:2048 nt
	global_load_dword v7, v[48:49], off offset:1024 nt
	v_mov_b32_e32 v46, 0
	s_cmpk_gt_u32 s5, 0xdf
	v_mov_b32_e32 v49, 0
	v_mov_b32_e32 v50, 0
	s_cbranch_scc1 .LBB0_1265
	s_add_i32 s25, s19, s4
	s_add_i32 s25, s25, 37
	v_mad_i64_i32 v[48:49], s[28:29], s25, v94, v[24:25]
	v_add_co_u32_e32 v56, vcc, 0x2000, v48
	s_nop 1
	v_addc_co_u32_e32 v57, vcc, 0, v49, vcc
	global_load_dword v49, v[48:49], off nt
	s_nop 0
	global_load_dword v50, v[56:57], off offset:3072 nt
.LBB0_1265:
	v_add_co_u32_e32 v56, vcc, 0x15939000, v28
	s_cmpk_gt_u32 s5, 0xde
	s_nop 0
	v_addc_co_u32_e32 v57, vcc, 0, v29, vcc
	v_add_co_u32_e32 v64, vcc, 0x1593b000, v28
	s_nop 1
	v_addc_co_u32_e32 v65, vcc, 0, v29, vcc
	global_load_dword v55, v[56:57], off nt
	s_nop 0
	global_load_dword v56, v[64:65], off offset:3072 nt
	v_mov_b32_e32 v64, 0
	s_cbranch_scc1 .LBB0_1267
	s_add_i32 s25, s19, s4
	s_add_i32 s25, s25, 38
	v_mad_i64_i32 v[46:47], s[28:29], s25, v94, v[24:25]
	v_add_co_u32_e32 v64, vcc, 0x2000, v46
	s_nop 1
	v_addc_co_u32_e32 v65, vcc, 0, v47, vcc
	global_load_dword v46, v[46:47], off nt
	s_nop 0
	global_load_dword v64, v[64:65], off offset:3072 nt
.LBB0_1267:
	v_add_co_u32_e32 v66, vcc, 0x1593e000, v28
	v_mov_b32_e32 v63, 0
	s_nop 0
	v_addc_co_u32_e32 v67, vcc, 0, v29, vcc
	v_add_co_u32_e32 v68, vcc, 0x15941000, v28
	s_cmpk_gt_u32 s5, 0xdd
	s_nop 0
	v_addc_co_u32_e32 v69, vcc, 0, v29, vcc
	global_load_dword v2, v[66:67], off offset:2048 nt
	global_load_dword v47, v[68:69], off offset:1024 nt
	v_mov_b32_e32 v57, 0
	v_mov_b32_e32 v61, 0
	s_cbranch_scc1 .LBB0_1269
	s_add_i32 s25, s19, s4
	s_add_i32 s25, s25, 39
	v_mad_i64_i32 v[66:67], s[28:29], s25, v94, v[24:25]
	v_add_co_u32_e32 v68, vcc, 0x2000, v66
	s_nop 1
	v_addc_co_u32_e32 v69, vcc, 0, v67, vcc
	global_load_dword v57, v[66:67], off nt
	global_load_dword v61, v[68:69], off offset:3072 nt
.LBB0_1269:
	v_add_co_u32_e32 v66, vcc, 0x15944000, v28
	s_cmpk_gt_u32 s5, 0xdc
	s_nop 0
	v_addc_co_u32_e32 v67, vcc, 0, v29, vcc
	v_add_co_u32_e32 v28, vcc, 0x15946000, v28
	s_nop 1
	v_addc_co_u32_e32 v29, vcc, 0, v29, vcc
	global_load_dword v65, v[66:67], off nt
	s_nop 0
	global_load_dword v66, v[28:29], off offset:3072 nt
	v_mov_b32_e32 v67, 0
	s_cbranch_scc1 .LBB0_1261
	s_add_i32 s5, s19, s4
	s_add_i32 s5, s5, 40
	v_mad_i64_i32 v[28:29], s[28:29], s5, v94, v[24:25]
	v_add_co_u32_e32 v68, vcc, 0x2000, v28
	s_nop 1
	v_addc_co_u32_e32 v69, vcc, 0, v29, vcc
	global_load_dword v67, v[28:29], off nt
	global_load_dword v63, v[68:69], off offset:3072 nt
	s_branch .LBB0_1261
.LBB0_1271:
	s_andn2_saveexec_b64 s[16:17], s[6:7]
	s_cbranch_execz .LBB0_1255
	v_ashrrev_i32_e32 v49, 31, v48
	v_lshlrev_b64 v[44:45], 2, v[48:49]
	v_lshl_add_u64 v[40:41], s[12:13], 0, v[44:45]
	v_add_co_u32_e32 v10, vcc, 0x5000, v40
	v_lshl_add_u64 v[50:51], s[26:27], 0, v[44:45]
	s_nop 0
	v_addc_co_u32_e32 v11, vcc, 0, v41, vcc
	v_add_co_u32_e32 v12, vcc, 0xb000, v40
	v_lshl_add_u64 v[48:49], v[48:49], 1, s[10:11]
	s_nop 0
	v_addc_co_u32_e32 v13, vcc, 0, v41, vcc
	v_add_co_u32_e32 v14, vcc, 0x10000, v40
	v_mov_b32_e32 v52, 0
	s_nop 0
	v_addc_co_u32_e32 v15, vcc, 0, v41, vcc
	v_add_co_u32_e32 v16, vcc, 0x16000, v40
	global_load_dwordx2 v[8:9], v[40:41], off
	s_nop 0
	global_load_dwordx2 v[10:11], v[10:11], off offset:2048
	s_nop 0
	global_load_dwordx2 v[12:13], v[12:13], off
	s_nop 0
	global_load_dwordx2 v[14:15], v[14:15], off offset:2048
	v_addc_co_u32_e32 v17, vcc, 0, v41, vcc
	v_add_co_u32_e32 v18, vcc, 0x1b000, v40
	v_mov_b32_e32 v53, 0
	s_nop 0
	v_addc_co_u32_e32 v19, vcc, 0, v41, vcc
	v_add_co_u32_e32 v20, vcc, 0x21000, v40
	s_waitcnt vmcnt(15)
	v_mov_b32_e32 v57, 0
	v_addc_co_u32_e32 v21, vcc, 0, v41, vcc
	v_add_co_u32_e32 v22, vcc, 0x26000, v40
	s_nop 1
	v_addc_co_u32_e32 v23, vcc, 0, v41, vcc
	v_add_co_u32_e32 v24, vcc, 0x2c000, v40
	global_load_dwordx2 v[16:17], v[16:17], off
	s_nop 0
	global_load_dwordx2 v[18:19], v[18:19], off offset:2048
	s_nop 0
	global_load_dwordx2 v[20:21], v[20:21], off
	s_nop 0
	global_load_dwordx2 v[22:23], v[22:23], off offset:2048
	v_addc_co_u32_e32 v25, vcc, 0, v41, vcc
	v_add_co_u32_e32 v26, vcc, 0x31000, v40
	s_nop 1
	v_addc_co_u32_e32 v27, vcc, 0, v41, vcc
	v_add_co_u32_e32 v28, vcc, 0x37000, v40
	s_nop 1
	v_addc_co_u32_e32 v29, vcc, 0, v41, vcc
	v_add_co_u32_e32 v30, vcc, 0x3c000, v40
	s_nop 1
	v_addc_co_u32_e32 v31, vcc, 0, v41, vcc
	v_add_co_u32_e32 v32, vcc, 0x42000, v40
	global_load_dwordx2 v[24:25], v[24:25], off
	s_nop 0
	global_load_dwordx2 v[26:27], v[26:27], off offset:2048
	s_nop 0
	global_load_dwordx2 v[28:29], v[28:29], off
	s_nop 0
	global_load_dwordx2 v[30:31], v[30:31], off offset:2048
	v_addc_co_u32_e32 v33, vcc, 0, v41, vcc
	v_add_co_u32_e32 v34, vcc, 0x47000, v40
	s_nop 1
	v_addc_co_u32_e32 v35, vcc, 0, v41, vcc
	v_add_co_u32_e32 v36, vcc, 0x4d000, v40
	s_nop 1
	v_addc_co_u32_e32 v37, vcc, 0, v41, vcc
	v_add_co_u32_e32 v38, vcc, 0x52000, v40
	s_nop 1
	v_addc_co_u32_e32 v39, vcc, 0, v41, vcc
	v_add_co_u32_e32 v42, vcc, 0x58000, v40
	global_load_dwordx2 v[32:33], v[32:33], off
	s_nop 0
	global_load_dwordx2 v[34:35], v[34:35], off offset:2048
	s_nop 0
	global_load_dwordx2 v[36:37], v[36:37], off
	s_nop 0
	global_load_dwordx2 v[38:39], v[38:39], off offset:2048
	v_addc_co_u32_e32 v43, vcc, 0, v41, vcc
	v_add_co_u32_e32 v46, vcc, 0x5d000, v40
	s_waitcnt vmcnt(26)
	s_nop 0
	v_addc_co_u32_e32 v47, vcc, 0, v41, vcc
	global_load_dwordx2 v[40:41], v[42:43], off
	s_nop 0
	global_load_dwordx2 v[42:43], v[46:47], off offset:2048
	v_lshl_add_u64 v[46:47], s[14:15], 0, v[44:45]
	global_load_dwordx2 v[44:45], v[46:47], off
	s_nop 0
	global_load_dwordx2 v[46:47], v[50:51], off
	s_andn2_b64 vcc, exec, s[76:77]
	s_cbranch_vccnz .LBB0_1274
	v_readlane_b32 s4, v232, 29
	v_readlane_b32 s5, v232, 30
	s_nop 1
	v_lshl_add_u64 v[50:51], v[48:49], 0, s[4:5]
	v_add_co_u32_e32 v54, vcc, 0x2000, v50
	s_nop 1
	v_addc_co_u32_e32 v55, vcc, 0, v51, vcc
	global_load_dword v53, v[50:51], off nt
	global_load_dword v57, v[54:55], off offset:3072 nt
.LBB0_1274:
	s_andn2_b64 vcc, exec, s[74:75]
	v_mov_b32_e32 v56, 0
	v_mov_b32_e32 v60, 0
	v_mov_b32_e32 v58, 0
	s_cbranch_vccnz .LBB0_1276
	v_readlane_b32 s4, v232, 31
	v_readlane_b32 s5, v232, 32
	s_nop 1
	v_lshl_add_u64 v[50:51], v[48:49], 0, s[4:5]
	v_readlane_b32 s4, v232, 33
	v_readlane_b32 s5, v232, 34
	v_add_co_u32_e32 v58, vcc, 0x2000, v50
	s_nop 0
	v_lshl_add_u64 v[54:55], v[48:49], 0, s[4:5]
	v_addc_co_u32_e32 v59, vcc, 0, v51, vcc
	v_add_co_u32_e32 v60, vcc, 0x2000, v54
	s_nop 1
	v_addc_co_u32_e32 v61, vcc, 0, v55, vcc
	global_load_dword v56, v[50:51], off nt
	s_nop 0
	global_load_dword v58, v[58:59], off offset:3072 nt
	s_nop 0
	global_load_dword v60, v[60:61], off offset:3072 nt
	s_nop 0
	global_load_dword v52, v[54:55], off nt
.LBB0_1276:
	v_mov_b32_e32 v59, 0
	s_andn2_b64 vcc, exec, s[84:85]
	v_mov_b32_e32 v54, 0
	v_mov_b32_e32 v55, 0
	s_cbranch_vccnz .LBB0_1278
	v_readlane_b32 s4, v232, 35
	v_readlane_b32 s5, v232, 36
	s_nop 1
	v_lshl_add_u64 v[50:51], v[48:49], 0, s[4:5]
	v_add_co_u32_e32 v62, vcc, 0x2000, v50
	s_waitcnt vmcnt(28)
	s_nop 0
	v_addc_co_u32_e32 v63, vcc, 0, v51, vcc
	global_load_dword v54, v[50:51], off nt
	global_load_dword v55, v[62:63], off offset:3072 nt
.LBB0_1278:
	v_cndmask_b32_e64 v2, 0, 1, s[68:69]
	v_cmp_ne_u32_e64 s[6:7], 1, v2
	s_andn2_b64 vcc, exec, s[68:69]
	v_mov_b32_e32 v72, 0
	s_cbranch_vccnz .LBB0_1280
	v_readlane_b32 s4, v232, 37
	v_readlane_b32 s5, v232, 38
	s_nop 1
	v_lshl_add_u64 v[50:51], v[48:49], 0, s[4:5]
	v_add_co_u32_e32 v62, vcc, 0x2000, v50
	s_waitcnt vmcnt(28)
	s_nop 0
	v_addc_co_u32_e32 v63, vcc, 0, v51, vcc
	global_load_dword v72, v[62:63], off offset:3072 nt
	global_load_dword v59, v[50:51], off nt
.LBB0_1280:
	v_lshl_add_u64 v[50:51], v[48:49], 0, s[86:87]
	v_add_co_u32_e32 v64, vcc, 0x2000, v50
	s_waitcnt vmcnt(28)
	v_lshl_add_u64 v[66:67], v[48:49], 0, s[88:89]
	v_addc_co_u32_e32 v65, vcc, 0, v51, vcc
	v_add_co_u32_e32 v68, vcc, 0x2000, v66
	v_cndmask_b32_e64 v2, 0, 1, s[72:73]
	s_nop 0
	v_addc_co_u32_e32 v69, vcc, 0, v67, vcc
	global_load_dword v63, v[50:51], off nt
	global_load_dword v76, v[64:65], off offset:3072 nt
	global_load_dword v61, v[66:67], off nt
	global_load_dword v62, v[68:69], off offset:3072 nt
	v_mov_b32_e32 v73, 0
	v_cmp_ne_u32_e64 s[8:9], 1, v2
	s_andn2_b64 vcc, exec, s[72:73]
	v_mov_b32_e32 v65, 0
	v_mov_b32_e32 v66, 0
	s_cbranch_vccnz .LBB0_1282
	v_readlane_b32 s4, v232, 39
	v_readlane_b32 s5, v232, 40
	s_nop 1
	v_lshl_add_u64 v[50:51], v[48:49], 0, s[4:5]
	v_add_co_u32_e32 v66, vcc, 0x2000, v50
	s_nop 1
	v_addc_co_u32_e32 v67, vcc, 0, v51, vcc
	global_load_dword v65, v[50:51], off nt
	s_nop 0
	global_load_dword v66, v[66:67], off offset:3072 nt
.LBB0_1282:
	s_and_b64 vcc, exec, s[6:7]
	v_mov_b32_e32 v75, 0
	s_cbranch_vccnz .LBB0_1284
	v_readlane_b32 s4, v232, 41
	v_readlane_b32 s5, v232, 42
	s_nop 1
	v_lshl_add_u64 v[50:51], v[48:49], 0, s[4:5]
	v_add_co_u32_e32 v68, vcc, 0x2000, v50
	s_nop 1
	v_addc_co_u32_e32 v69, vcc, 0, v51, vcc
	global_load_dword v75, v[68:69], off offset:3072 nt
	global_load_dword v73, v[50:51], off nt
.LBB0_1284:
	v_lshl_add_u64 v[50:51], v[48:49], 0, s[94:95]
	v_add_co_u32_e32 v68, vcc, 0x2000, v50
	v_lshl_add_u64 v[70:71], v[48:49], 0, s[96:97]
	s_nop 0
	v_addc_co_u32_e32 v69, vcc, 0, v51, vcc
	v_add_co_u32_e32 v78, vcc, 0x2000, v70
	v_mov_b32_e32 v64, 0
	s_nop 0
	v_addc_co_u32_e32 v79, vcc, 0, v71, vcc
	global_load_dword v83, v[50:51], off nt
	global_load_dword v86, v[68:69], off offset:3072 nt
	global_load_dword v82, v[70:71], off nt
	global_load_dword v81, v[78:79], off offset:3072 nt
	s_and_b64 vcc, exec, s[8:9]
	v_mov_b32_e32 v77, 0
	v_mov_b32_e32 v80, 0
	s_cbranch_vccnz .LBB0_1286
	v_readlane_b32 s4, v232, 43
	v_readlane_b32 s5, v232, 44
	s_nop 1
	v_lshl_add_u64 v[50:51], v[48:49], 0, s[4:5]
	v_add_co_u32_e32 v68, vcc, 0x2000, v50
	s_nop 1
	v_addc_co_u32_e32 v69, vcc, 0, v51, vcc
	global_load_dword v77, v[50:51], off nt
	global_load_dword v80, v[68:69], off offset:3072 nt
.LBB0_1286:
	s_and_b64 vcc, exec, s[6:7]
	v_mov_b32_e32 v68, 0
	s_cbranch_vccnz .LBB0_1288
	v_readlane_b32 s4, v232, 45
	v_readlane_b32 s5, v232, 46
	s_nop 1
	v_lshl_add_u64 v[50:51], v[48:49], 0, s[4:5]
	v_add_co_u32_e32 v68, vcc, 0x2000, v50
	s_nop 1
	v_addc_co_u32_e32 v69, vcc, 0, v51, vcc
	global_load_dword v68, v[68:69], off offset:3072 nt
	s_nop 0
	global_load_dword v64, v[50:51], off nt
.LBB0_1288:
	v_lshl_add_u64 v[50:51], v[48:49], 0, s[38:39]
	v_add_co_u32_e32 v70, vcc, 0x2000, v50
	v_lshl_add_u64 v[78:79], v[48:49], 0, s[36:37]
	s_nop 0
	v_addc_co_u32_e32 v71, vcc, 0, v51, vcc
	v_add_co_u32_e32 v84, vcc, 0x2000, v78
	v_mov_b32_e32 v2, 0
	s_nop 0
	v_addc_co_u32_e32 v85, vcc, 0, v79, vcc
	global_load_dword v67, v[50:51], off nt
	s_nop 0
	global_load_dword v70, v[70:71], off offset:3072 nt
	s_nop 0
	global_load_dword v69, v[78:79], off nt
	global_load_dword v71, v[84:85], off offset:3072 nt
	s_and_b64 vcc, exec, s[8:9]
	v_mov_b32_e32 v134, 0
	v_mov_b32_e32 v132, 0
	s_cbranch_vccnz .LBB0_1290
	v_readlane_b32 s4, v232, 47
	v_readlane_b32 s5, v232, 48
	s_nop 1
	v_lshl_add_u64 v[50:51], v[48:49], 0, s[4:5]
	v_add_co_u32_e32 v78, vcc, 0x2000, v50
	s_nop 1
	v_addc_co_u32_e32 v79, vcc, 0, v51, vcc
	global_load_dword v134, v[50:51], off nt
	global_load_dword v132, v[78:79], off offset:3072 nt
.LBB0_1290:
	s_and_b64 vcc, exec, s[6:7]
	v_mov_b32_e32 v97, 0
	s_cbranch_vccnz .LBB0_1292
	v_readlane_b32 s4, v232, 49
	v_readlane_b32 s5, v232, 50
	s_nop 1
	v_lshl_add_u64 v[50:51], v[48:49], 0, s[4:5]
	v_add_co_u32_e32 v78, vcc, 0x2000, v50
	s_nop 1
	v_addc_co_u32_e32 v79, vcc, 0, v51, vcc
	global_load_dword v97, v[78:79], off offset:3072 nt
	global_load_dword v2, v[50:51], off nt
.LBB0_1292:
	v_lshl_add_u64 v[50:51], v[48:49], 0, s[34:35]
	v_add_co_u32_e32 v78, vcc, 0x2000, v50
	v_lshl_add_u64 v[84:85], v[48:49], 0, s[0:1]
	s_nop 0
	v_addc_co_u32_e32 v79, vcc, 0, v51, vcc
	v_add_co_u32_e32 v88, vcc, 0x2000, v84
	v_mov_b32_e32 v126, 0
	s_nop 0
	v_addc_co_u32_e32 v89, vcc, 0, v85, vcc
	global_load_dword v112, v[50:51], off nt
	global_load_dword v113, v[78:79], off offset:3072 nt
	global_load_dword v99, v[84:85], off nt
	global_load_dword v115, v[88:89], off offset:3072 nt
	s_and_b64 vcc, exec, s[8:9]
	v_mov_b32_e32 v127, 0
	v_mov_b32_e32 v130, 0
	s_cbranch_vccnz .LBB0_1294
	v_readlane_b32 s4, v232, 51
	v_readlane_b32 s5, v232, 52
	s_nop 1
	v_lshl_add_u64 v[50:51], v[48:49], 0, s[4:5]
	v_add_co_u32_e32 v78, vcc, 0x2000, v50
	s_nop 1
	v_addc_co_u32_e32 v79, vcc, 0, v51, vcc
	global_load_dword v127, v[50:51], off nt
	global_load_dword v130, v[78:79], off offset:3072 nt
.LBB0_1294:
	s_and_b64 vcc, exec, s[6:7]
	v_mov_b32_e32 v136, 0
	s_cbranch_vccnz .LBB0_1296
	v_readlane_b32 s4, v232, 53
	v_readlane_b32 s5, v232, 54
	s_nop 1
	v_lshl_add_u64 v[50:51], v[48:49], 0, s[4:5]
	v_add_co_u32_e32 v78, vcc, 0x2000, v50
	s_nop 1
	v_addc_co_u32_e32 v79, vcc, 0, v51, vcc
	global_load_dword v136, v[78:79], off offset:3072 nt
	global_load_dword v126, v[50:51], off nt
.LBB0_1296:
	v_lshl_add_u64 v[50:51], v[48:49], 0, s[78:79]
	v_add_co_u32_e32 v78, vcc, 0x2000, v50
	v_lshl_add_u64 v[84:85], v[48:49], 0, s[80:81]
	s_nop 0
	v_addc_co_u32_e32 v79, vcc, 0, v51, vcc
	v_add_co_u32_e32 v88, vcc, 0x2000, v84
	v_mov_b32_e32 v142, 0
	s_nop 0
	v_addc_co_u32_e32 v89, vcc, 0, v85, vcc
	global_load_dword v137, v[50:51], off nt
	global_load_dword v139, v[78:79], off offset:3072 nt
	global_load_dword v138, v[84:85], off nt
	global_load_dword v141, v[88:89], off offset:3072 nt
	s_and_b64 vcc, exec, s[8:9]
	v_mov_b32_e32 v140, 0
	s_cbranch_vccnz .LBB0_1298
	v_readlane_b32 s4, v232, 55
	v_readlane_b32 s5, v232, 56
	s_nop 1
	v_lshl_add_u64 v[50:51], v[48:49], 0, s[4:5]
	v_add_co_u32_e32 v78, vcc, 0x2000, v50
	s_nop 1
	v_addc_co_u32_e32 v79, vcc, 0, v51, vcc
	global_load_dword v142, v[50:51], off nt
	global_load_dword v140, v[78:79], off offset:3072 nt

.LBB0_1300:
	s_waitcnt vmcnt(9)
	v_mov_b32_e32 v102, v97
	s_waitcnt vmcnt(6)
	v_mov_b32_e32 v104, v113
	s_waitcnt vmcnt(4)
	v_mov_b32_e32 v105, v115
	v_mov_b32_e32 v107, v130
	v_mov_b32_e32 v108, v136
	s_waitcnt vmcnt(2)
	v_mov_b32_e32 v109, v139
	s_waitcnt vmcnt(0)
	v_mov_b32_e32 v110, v141
	v_mov_b32_e32 v111, v140
	v_mov_b32_e32 v116, v2
	v_mov_b32_e32 v117, v112
	v_mov_b32_e32 v118, v99
	v_mov_b32_e32 v119, v127
	v_mov_b32_e32 v120, v126
	v_mov_b32_e32 v121, v137
	v_mov_b32_e32 v122, v138
	s_cmp_eq_u32 s25, 28
	v_mov_b32_e32 v125, v142
	s_cbranch_scc1 .LBB0_1299
	s_add_i32 s30, s22, s25
	s_add_i32 s30, s30, 5
	s_cmp_gt_u32 s30, 63
	s_cselect_b64 s[4:5], -1, 0
	s_cmp_lt_u32 s30, 64
	s_cselect_b64 s[28:29], -1, 0
	s_or_b64 vcc, s[66:67], s[4:5]
	v_mov_b32_e32 v7, 0
	s_and_b64 vcc, exec, vcc
	v_mov_b32_e32 v5, 0
	v_mov_b32_e32 v96, 0
	s_cbranch_vccnz .LBB0_1303
	s_add_i32 s31, s23, s25
	s_addk_i32 s31, 0xfc5
	v_mad_i64_i32 v[78:79], vcc, s31, v94, v[48:49]
	v_add_co_u32_e32 v84, vcc, 0x2000, v78
	s_nop 1
	v_addc_co_u32_e32 v85, vcc, 0, v79, vcc
	global_load_dword v5, v[78:79], off nt
	global_load_dword v96, v[84:85], off offset:3072 nt
.LBB0_1303:
	s_andn2_b64 vcc, exec, s[28:29]
	v_mov_b32_e32 v98, 0
	v_mov_b32_e32 v101, 0
	v_mov_b32_e32 v100, 0
	s_cbranch_vccnz .LBB0_1305
	s_add_i32 s31, s23, s25
	s_add_i32 s28, s31, 0x1005
	v_mad_i64_i32 v[78:79], s[28:29], s28, v94, v[48:49]
	v_add_co_u32_e32 v84, vcc, 0x2000, v78
	s_addk_i32 s31, 0x1045
	s_nop 0
	v_addc_co_u32_e32 v85, vcc, 0, v79, vcc
	v_mad_i64_i32 v[88:89], s[28:29], s31, v94, v[48:49]
	v_add_co_u32_e32 v90, vcc, 0x2000, v88
	s_nop 1
	v_addc_co_u32_e32 v91, vcc, 0, v89, vcc
	global_load_dword v98, v[78:79], off nt
	global_load_dword v100, v[84:85], off offset:3072 nt
	global_load_dword v7, v[88:89], off nt
	global_load_dword v101, v[90:91], off offset:3072 nt
.LBB0_1305:
	s_or_b64 s[4:5], s[70:71], s[4:5]
	v_mov_b32_e32 v103, 0
	s_and_b64 vcc, exec, s[4:5]
	v_mov_b32_e32 v106, 0
	v_mov_b32_e32 v114, 0
	s_cbranch_vccnz .LBB0_1307
	s_add_i32 s4, s23, s25
	s_addk_i32 s4, 0x1085
	v_mad_i64_i32 v[78:79], s[4:5], s4, v94, v[48:49]
	v_add_co_u32_e32 v84, vcc, 0x2000, v78
	s_nop 1
	v_addc_co_u32_e32 v85, vcc, 0, v79, vcc
	global_load_dword v106, v[78:79], off nt
	global_load_dword v114, v[84:85], off offset:3072 nt
.LBB0_1307:
	s_cmp_gt_u32 s30, 62
	s_cselect_b64 s[4:5], -1, 0
	s_cmp_lt_u32 s30, 63
	s_cselect_b64 s[28:29], -1, 0
	s_or_b64 vcc, s[66:67], s[4:5]
	s_and_b64 vcc, exec, vcc
	v_mov_b32_e32 v123, 0
	s_cbranch_vccnz .LBB0_1309
	s_add_i32 s31, s23, s25
	s_addk_i32 s31, 0xfc6
	v_mad_i64_i32 v[78:79], vcc, s31, v94, v[48:49]
	v_add_co_u32_e32 v84, vcc, 0x2000, v78
	s_nop 1
	v_addc_co_u32_e32 v85, vcc, 0, v79, vcc
	global_load_dword v103, v[78:79], off nt
	global_load_dword v123, v[84:85], off offset:3072 nt
.LBB0_1309:
	v_mov_b32_e32 v124, 0
	s_andn2_b64 vcc, exec, s[28:29]
	v_mov_b32_e32 v129, 0
	v_mov_b32_e32 v128, 0
	v_mov_b32_e32 v133, 0
	v_mov_b32_e32 v131, 0
	s_cbranch_vccnz .LBB0_1311
	s_add_i32 s31, s23, s25
	s_add_i32 s28, s31, 0x1006
	v_mad_i64_i32 v[78:79], s[28:29], s28, v94, v[48:49]
	v_add_co_u32_e32 v84, vcc, 0x2000, v78
	s_addk_i32 s31, 0x1046
	s_nop 0
	v_addc_co_u32_e32 v85, vcc, 0, v79, vcc
	v_mad_i64_i32 v[88:89], s[28:29], s31, v94, v[48:49]
	v_add_co_u32_e32 v90, vcc, 0x2000, v88
	s_nop 1
	v_addc_co_u32_e32 v91, vcc, 0, v89, vcc
	global_load_dword v128, v[78:79], off nt
	global_load_dword v131, v[84:85], off offset:3072 nt
	global_load_dword v129, v[88:89], off nt
	global_load_dword v133, v[90:91], off offset:3072 nt
.LBB0_1311:
	s_or_b64 s[4:5], s[70:71], s[4:5]
	s_and_b64 vcc, exec, s[4:5]
	v_mov_b32_e32 v135, 0
	s_cbranch_vccnz .LBB0_1313
	s_add_i32 s4, s23, s25
	s_addk_i32 s4, 0x1086
	v_mad_i64_i32 v[78:79], s[4:5], s4, v94, v[48:49]
	v_add_co_u32_e32 v84, vcc, 0x2000, v78
	s_nop 1
	v_addc_co_u32_e32 v85, vcc, 0, v79, vcc
	global_load_dword v124, v[78:79], off nt
	global_load_dword v135, v[84:85], off offset:3072 nt
.LBB0_1313:
	s_cmp_gt_u32 s30, 61
	s_cselect_b64 s[4:5], -1, 0
	s_cmp_lt_u32 s30, 62
	s_cselect_b64 s[28:29], -1, 0
	s_or_b64 vcc, s[66:67], s[4:5]
	v_mov_b32_e32 v99, 0
	s_and_b64 vcc, exec, vcc
	v_mov_b32_e32 v2, 0
	v_mov_b32_e32 v97, 0
	s_cbranch_vccnz .LBB0_1315
	s_add_i32 s31, s23, s25
	s_addk_i32 s31, 0xfc7
	v_mad_i64_i32 v[78:79], vcc, s31, v94, v[48:49]
	v_add_co_u32_e32 v84, vcc, 0x2000, v78
	s_nop 1
	v_addc_co_u32_e32 v85, vcc, 0, v79, vcc
	global_load_dword v2, v[78:79], off nt
	global_load_dword v97, v[84:85], off offset:3072 nt
.LBB0_1315:
	s_andn2_b64 vcc, exec, s[28:29]
	v_mov_b32_e32 v112, 0
	v_mov_b32_e32 v115, 0
	v_mov_b32_e32 v113, 0
	s_cbranch_vccnz .LBB0_1317
	s_add_i32 s31, s23, s25
	s_add_i32 s28, s31, 0x1007
	v_mad_i64_i32 v[78:79], s[28:29], s28, v94, v[48:49]
	v_add_co_u32_e32 v84, vcc, 0x2000, v78
	s_addk_i32 s31, 0x1047
	s_nop 0
	v_addc_co_u32_e32 v85, vcc, 0, v79, vcc
	v_mad_i64_i32 v[88:89], s[28:29], s31, v94, v[48:49]
	v_add_co_u32_e32 v90, vcc, 0x2000, v88
	s_nop 1
	v_addc_co_u32_e32 v91, vcc, 0, v89, vcc
	global_load_dword v112, v[78:79], off nt
	global_load_dword v113, v[84:85], off offset:3072 nt
	global_load_dword v99, v[88:89], off nt
	global_load_dword v115, v[90:91], off offset:3072 nt
.LBB0_1317:
	s_or_b64 s[4:5], s[70:71], s[4:5]
	v_mov_b32_e32 v126, 0
	s_and_b64 vcc, exec, s[4:5]
	v_mov_b32_e32 v127, 0
	v_mov_b32_e32 v130, 0
	s_cbranch_vccnz .LBB0_1319
	s_add_i32 s4, s23, s25
	s_addk_i32 s4, 0x1087
	v_mad_i64_i32 v[78:79], s[4:5], s4, v94, v[48:49]
	v_add_co_u32_e32 v84, vcc, 0x2000, v78
	s_nop 1
	v_addc_co_u32_e32 v85, vcc, 0, v79, vcc
	global_load_dword v127, v[78:79], off nt
	global_load_dword v130, v[84:85], off offset:3072 nt
.LBB0_1319:
	s_cmp_gt_u32 s30, 60
	s_cselect_b64 s[4:5], -1, 0
	s_cmp_lt_u32 s30, 61
	s_cselect_b64 s[28:29], -1, 0
	s_or_b64 s[30:31], s[66:67], s[4:5]
	s_and_b64 vcc, exec, s[30:31]
	v_mov_b32_e32 v136, 0
	s_cbranch_vccnz .LBB0_1321
	s_add_i32 s30, s23, s25
	s_addk_i32 s30, 0xfc8
	v_mad_i64_i32 v[78:79], s[30:31], s30, v94, v[48:49]
	v_add_co_u32_e32 v84, vcc, 0x2000, v78
	s_nop 1
	v_addc_co_u32_e32 v85, vcc, 0, v79, vcc
	global_load_dword v126, v[78:79], off nt
	global_load_dword v136, v[84:85], off offset:3072 nt
.LBB0_1321:
	v_mov_b32_e32 v140, 0
	s_andn2_b64 vcc, exec, s[28:29]
	v_mov_b32_e32 v138, 0
	v_mov_b32_e32 v137, 0
	v_mov_b32_e32 v141, 0
	v_mov_b32_e32 v139, 0
	s_cbranch_vccnz .LBB0_1323
	s_add_i32 s30, s23, s25
	s_add_i32 s28, s30, 0x1008
	v_mad_i64_i32 v[78:79], s[28:29], s28, v94, v[48:49]
	v_add_co_u32_e32 v84, vcc, 0x2000, v78
	s_addk_i32 s30, 0x1048
	s_nop 0
	v_addc_co_u32_e32 v85, vcc, 0, v79, vcc
	v_mad_i64_i32 v[88:89], s[28:29], s30, v94, v[48:49]
	v_add_co_u32_e32 v90, vcc, 0x2000, v88
	s_nop 1
	v_addc_co_u32_e32 v91, vcc, 0, v89, vcc
	global_load_dword v137, v[78:79], off nt
	global_load_dword v139, v[84:85], off offset:3072 nt
	global_load_dword v138, v[88:89], off nt
	global_load_dword v141, v[90:91], off offset:3072 nt
.LBB0_1323:
	s_or_b64 s[4:5], s[70:71], s[4:5]
	s_and_b64 vcc, exec, s[4:5]
	v_mov_b32_e32 v142, 0
	s_cbranch_vccnz .LBB0_1299
	s_add_i32 s4, s23, s25
	s_addk_i32 s4, 0x1088
	v_mad_i64_i32 v[78:79], s[4:5], s4, v94, v[48:49]
	v_add_co_u32_e32 v84, vcc, 0x2000, v78
	s_nop 1
	v_addc_co_u32_e32 v85, vcc, 0, v79, vcc
	global_load_dword v142, v[78:79], off nt
	global_load_dword v140, v[84:85], off offset:3072 nt
	s_branch .LBB0_1299

.LBB0_2493:
	s_movk_i32 s4, 0x2bf
	v_cmp_lt_i32_e32 vcc, s4, v95
	v_add_lshl_u32 v48, v95, s22, 1
	s_and_saveexec_b64 s[4:5], vcc
	s_xor_b64 s[6:7], exec, s[4:5]
	s_cbranch_execz .LBB0_2508
	v_add_u32_e32 v2, 0xfffffa80, v48
	v_readlane_b32 s4, v232, 17
	v_lshlrev_b64 v[20:21], 2, v[2:3]
	v_readlane_b32 s5, v232, 18
	v_lshl_add_u64 v[22:23], s[14:15], 0, v[20:21]
	v_lshl_add_u64 v[24:25], s[26:27], 0, v[20:21]
	v_lshl_add_u64 v[8:9], s[4:5], 0, v[20:21]
	v_readlane_b32 s4, v232, 19
	v_add_co_u32_e32 v10, vcc, 0x5000, v8
	v_readlane_b32 s5, v232, 20
	s_nop 0
	v_addc_co_u32_e32 v11, vcc, 0, v9, vcc
	v_lshl_add_u64 v[12:13], s[4:5], 0, v[20:21]
	v_readlane_b32 s4, v232, 21
	v_add_co_u32_e32 v14, vcc, 0x5000, v12
	v_readlane_b32 s5, v232, 22
	s_nop 0
	v_addc_co_u32_e32 v15, vcc, 0, v13, vcc
	v_lshl_add_u64 v[16:17], s[4:5], 0, v[20:21]
	global_load_dwordx2 v[8:9], v[8:9], off
	s_nop 0
	global_load_dwordx2 v[10:11], v[10:11], off offset:2048
	s_nop 0
	global_load_dwordx2 v[12:13], v[12:13], off
	s_nop 0
	global_load_dwordx2 v[14:15], v[14:15], off offset:2048
	v_add_co_u32_e32 v18, vcc, 0x5000, v16
	s_nop 1
	v_addc_co_u32_e32 v19, vcc, 0, v17, vcc
	global_load_dwordx2 v[16:17], v[16:17], off
	s_nop 0
	global_load_dwordx2 v[18:19], v[18:19], off offset:2048
	s_nop 0
	global_load_dwordx2 v[20:21], v[22:23], off
	s_nop 0
	global_load_dwordx2 v[22:23], v[24:25], off
	s_andn2_b64 vcc, exec, s[30:31]
	v_lshl_add_u64 v[24:25], v[2:3], 1, s[10:11]
	s_cbranch_vccnz .LBB0_2496
	v_readlane_b32 s4, v232, 27
	v_readlane_b32 s5, v232, 28
	s_nop 1
	v_lshl_add_u64 v[26:27], v[24:25], 0, s[4:5]
	v_add_co_u32_e32 v28, vcc, 0x2000, v26
	s_nop 1
	v_addc_co_u32_e32 v29, vcc, 0, v27, vcc
	global_load_dword v30, v[26:27], off nt
	global_load_dword v31, v[28:29], off offset:3072 nt
	s_branch .LBB0_2497

.LBB0_2499:
	s_waitcnt vmcnt(6)
	v_mov_b32_e32 v51, v47
	s_waitcnt vmcnt(4)
	v_mov_b32_e32 v52, v61
	s_waitcnt vmcnt(2)
	v_mov_b32_e32 v53, v66
	s_waitcnt vmcnt(1)
	v_mov_b32_e32 v54, v63
	v_mov_b32_e32 v58, v2
	v_mov_b32_e32 v59, v57
	v_mov_b32_e32 v60, v65
	s_cmp_eq_u32 s4, 28
	s_waitcnt vmcnt(0)
	v_mov_b32_e32 v62, v67
	s_cbranch_scc1 .LBB0_2498
	v_lshl_add_u64 v[28:29], s[8:9], 0, v[26:27]
	v_add_co_u32_e32 v46, vcc, 0x15933000, v28
	s_add_i32 s5, s12, s4
	s_nop 0
	v_addc_co_u32_e32 v47, vcc, 0, v29, vcc
	v_add_co_u32_e32 v48, vcc, 0x15936000, v28
	s_add_i32 s5, s5, 5
	s_nop 0
	v_addc_co_u32_e32 v49, vcc, 0, v29, vcc
	global_load_dword v5, v[46:47], off offset:2048 nt
	global_load_dword v7, v[48:49], off offset:1024 nt
	v_mov_b32_e32 v46, 0
	s_cmpk_gt_u32 s5, 0xdf
	v_mov_b32_e32 v49, 0
	v_mov_b32_e32 v50, 0
	s_cbranch_scc1 .LBB0_2502
	s_add_i32 s23, s13, s4
	s_add_i32 s23, s23, 37
	v_mad_i64_i32 v[48:49], s[24:25], s23, v94, v[24:25]
	v_add_co_u32_e32 v56, vcc, 0x2000, v48
	s_nop 1
	v_addc_co_u32_e32 v57, vcc, 0, v49, vcc
	global_load_dword v49, v[48:49], off nt
	s_nop 0
	global_load_dword v50, v[56:57], off offset:3072 nt
.LBB0_2502:
	v_add_co_u32_e32 v56, vcc, 0x15939000, v28
	s_cmpk_gt_u32 s5, 0xde
	s_nop 0
	v_addc_co_u32_e32 v57, vcc, 0, v29, vcc
	v_add_co_u32_e32 v64, vcc, 0x1593b000, v28
	s_nop 1
	v_addc_co_u32_e32 v65, vcc, 0, v29, vcc
	global_load_dword v55, v[56:57], off nt
	s_nop 0
	global_load_dword v56, v[64:65], off offset:3072 nt
	v_mov_b32_e32 v64, 0
	s_cbranch_scc1 .LBB0_2504
	s_add_i32 s23, s13, s4
	s_add_i32 s23, s23, 38
	v_mad_i64_i32 v[46:47], s[24:25], s23, v94, v[24:25]
	v_add_co_u32_e32 v64, vcc, 0x2000, v46
	s_nop 1
	v_addc_co_u32_e32 v65, vcc, 0, v47, vcc
	global_load_dword v46, v[46:47], off nt
	s_nop 0
	global_load_dword v64, v[64:65], off offset:3072 nt
.LBB0_2504:
	v_add_co_u32_e32 v66, vcc, 0x1593e000, v28
	v_mov_b32_e32 v63, 0
	s_nop 0
	v_addc_co_u32_e32 v67, vcc, 0, v29, vcc
	v_add_co_u32_e32 v68, vcc, 0x15941000, v28
	s_cmpk_gt_u32 s5, 0xdd
	s_nop 0
	v_addc_co_u32_e32 v69, vcc, 0, v29, vcc
	global_load_dword v2, v[66:67], off offset:2048 nt
	global_load_dword v47, v[68:69], off offset:1024 nt
	v_mov_b32_e32 v57, 0
	v_mov_b32_e32 v61, 0
	s_cbranch_scc1 .LBB0_2506
	s_add_i32 s23, s13, s4
	s_add_i32 s23, s23, 39
	v_mad_i64_i32 v[66:67], s[24:25], s23, v94, v[24:25]
	v_add_co_u32_e32 v68, vcc, 0x2000, v66
	s_nop 1
	v_addc_co_u32_e32 v69, vcc, 0, v67, vcc
	global_load_dword v57, v[66:67], off nt
	global_load_dword v61, v[68:69], off offset:3072 nt
.LBB0_2506:
	v_add_co_u32_e32 v66, vcc, 0x15944000, v28
	s_cmpk_gt_u32 s5, 0xdc
	s_nop 0
	v_addc_co_u32_e32 v67, vcc, 0, v29, vcc
	v_add_co_u32_e32 v28, vcc, 0x15946000, v28
	s_nop 1
	v_addc_co_u32_e32 v29, vcc, 0, v29, vcc
	global_load_dword v65, v[66:67], off nt
	s_nop 0
	global_load_dword v66, v[28:29], off offset:3072 nt
	v_mov_b32_e32 v67, 0
	s_cbranch_scc1 .LBB0_2498
	s_add_i32 s5, s13, s4
	s_add_i32 s5, s5, 40
	v_mad_i64_i32 v[28:29], s[24:25], s5, v94, v[24:25]
	v_add_co_u32_e32 v68, vcc, 0x2000, v28
	s_nop 1
	v_addc_co_u32_e32 v69, vcc, 0, v29, vcc
	global_load_dword v67, v[28:29], off nt
	global_load_dword v63, v[68:69], off offset:3072 nt
	s_branch .LBB0_2498
.LBB0_2508:
	s_andn2_saveexec_b64 s[16:17], s[6:7]
	s_cbranch_execz .LBB0_2492
	v_ashrrev_i32_e32 v49, 31, v48
	v_readlane_b32 s4, v232, 25
	v_lshlrev_b64 v[44:45], 2, v[48:49]
	v_readlane_b32 s5, v232, 26
	v_lshl_add_u64 v[50:51], s[26:27], 0, v[44:45]
	v_lshl_add_u64 v[48:49], v[48:49], 1, s[10:11]
	v_lshl_add_u64 v[40:41], s[4:5], 0, v[44:45]
	v_add_co_u32_e32 v10, vcc, 0x5000, v40
	v_mov_b32_e32 v52, 0
	s_nop 0
	v_addc_co_u32_e32 v11, vcc, 0, v41, vcc
	v_add_co_u32_e32 v12, vcc, 0xb000, v40
	v_mov_b32_e32 v53, 0
	s_nop 0
	v_addc_co_u32_e32 v13, vcc, 0, v41, vcc
	v_add_co_u32_e32 v14, vcc, 0x10000, v40
	s_waitcnt vmcnt(11)
	v_mov_b32_e32 v57, 0
	v_addc_co_u32_e32 v15, vcc, 0, v41, vcc
	v_add_co_u32_e32 v16, vcc, 0x16000, v40
	global_load_dwordx2 v[8:9], v[40:41], off
	s_nop 0
	global_load_dwordx2 v[10:11], v[10:11], off offset:2048
	s_nop 0
	global_load_dwordx2 v[12:13], v[12:13], off
	s_nop 0
	global_load_dwordx2 v[14:15], v[14:15], off offset:2048
	v_addc_co_u32_e32 v17, vcc, 0, v41, vcc
	v_add_co_u32_e32 v18, vcc, 0x1b000, v40
	s_nop 1
	v_addc_co_u32_e32 v19, vcc, 0, v41, vcc
	v_add_co_u32_e32 v20, vcc, 0x21000, v40
	s_nop 1
	v_addc_co_u32_e32 v21, vcc, 0, v41, vcc
	v_add_co_u32_e32 v22, vcc, 0x26000, v40
	s_nop 1
	v_addc_co_u32_e32 v23, vcc, 0, v41, vcc
	v_add_co_u32_e32 v24, vcc, 0x2c000, v40
	global_load_dwordx2 v[16:17], v[16:17], off
	s_nop 0
	global_load_dwordx2 v[18:19], v[18:19], off offset:2048
	s_nop 0
	global_load_dwordx2 v[20:21], v[20:21], off
	s_nop 0
	global_load_dwordx2 v[22:23], v[22:23], off offset:2048
	v_addc_co_u32_e32 v25, vcc, 0, v41, vcc
	v_add_co_u32_e32 v26, vcc, 0x31000, v40
	s_nop 1
	v_addc_co_u32_e32 v27, vcc, 0, v41, vcc
	v_add_co_u32_e32 v28, vcc, 0x37000, v40
	s_nop 1
	v_addc_co_u32_e32 v29, vcc, 0, v41, vcc
	v_add_co_u32_e32 v30, vcc, 0x3c000, v40
	s_nop 1
	v_addc_co_u32_e32 v31, vcc, 0, v41, vcc
	v_add_co_u32_e32 v32, vcc, 0x42000, v40
	global_load_dwordx2 v[24:25], v[24:25], off
	s_nop 0
	global_load_dwordx2 v[26:27], v[26:27], off offset:2048
	s_nop 0
	global_load_dwordx2 v[28:29], v[28:29], off
	s_nop 0
	global_load_dwordx2 v[30:31], v[30:31], off offset:2048
	v_addc_co_u32_e32 v33, vcc, 0, v41, vcc
	v_add_co_u32_e32 v34, vcc, 0x47000, v40
	s_nop 1
	v_addc_co_u32_e32 v35, vcc, 0, v41, vcc
	v_add_co_u32_e32 v36, vcc, 0x4d000, v40
	s_nop 1
	v_addc_co_u32_e32 v37, vcc, 0, v41, vcc
	v_add_co_u32_e32 v38, vcc, 0x52000, v40
	s_nop 1
	v_addc_co_u32_e32 v39, vcc, 0, v41, vcc
	v_add_co_u32_e32 v42, vcc, 0x58000, v40
	global_load_dwordx2 v[32:33], v[32:33], off
	s_nop 0
	global_load_dwordx2 v[34:35], v[34:35], off offset:2048
	s_nop 0
	global_load_dwordx2 v[36:37], v[36:37], off
	s_nop 0
	global_load_dwordx2 v[38:39], v[38:39], off offset:2048
	v_addc_co_u32_e32 v43, vcc, 0, v41, vcc
	v_add_co_u32_e32 v46, vcc, 0x5d000, v40
	s_waitcnt vmcnt(26)
	s_nop 0
	v_addc_co_u32_e32 v47, vcc, 0, v41, vcc
	global_load_dwordx2 v[40:41], v[42:43], off
	s_nop 0
	global_load_dwordx2 v[42:43], v[46:47], off offset:2048
	v_lshl_add_u64 v[46:47], s[14:15], 0, v[44:45]
	global_load_dwordx2 v[44:45], v[46:47], off
	s_nop 0
	global_load_dwordx2 v[46:47], v[50:51], off
	s_andn2_b64 vcc, exec, s[76:77]
	s_cbranch_vccnz .LBB0_2511
	v_readlane_b32 s4, v232, 29
	v_readlane_b32 s5, v232, 30
	s_nop 1
	v_lshl_add_u64 v[50:51], v[48:49], 0, s[4:5]
	v_add_co_u32_e32 v54, vcc, 0x2000, v50
	s_nop 1
	v_addc_co_u32_e32 v55, vcc, 0, v51, vcc
	global_load_dword v53, v[50:51], off nt
	global_load_dword v57, v[54:55], off offset:3072 nt

.LBB0_2537:
	s_waitcnt vmcnt(9)
	v_mov_b32_e32 v102, v97
	s_waitcnt vmcnt(6)
	v_mov_b32_e32 v104, v113
	s_waitcnt vmcnt(4)
	v_mov_b32_e32 v105, v115
	v_mov_b32_e32 v107, v130
	v_mov_b32_e32 v108, v136
	s_waitcnt vmcnt(2)
	v_mov_b32_e32 v109, v139
	s_waitcnt vmcnt(0)
	v_mov_b32_e32 v110, v141
	v_mov_b32_e32 v111, v140
	v_mov_b32_e32 v116, v2
	v_mov_b32_e32 v117, v112
	v_mov_b32_e32 v118, v99
	v_mov_b32_e32 v119, v127
	v_mov_b32_e32 v120, v126
	v_mov_b32_e32 v121, v137
	v_mov_b32_e32 v122, v138
	s_cmp_eq_u32 s23, 28
	v_mov_b32_e32 v125, v142
	s_cbranch_scc1 .LBB0_2536
	s_add_i32 s24, s18, s23
	s_add_i32 s24, s24, 5
	s_cmp_gt_u32 s24, 63
	s_cselect_b64 s[4:5], -1, 0
	s_cmp_lt_u32 s24, 64
	s_cselect_b64 s[28:29], -1, 0
	s_or_b64 vcc, s[66:67], s[4:5]
	v_mov_b32_e32 v7, 0
	s_and_b64 vcc, exec, vcc
	v_mov_b32_e32 v5, 0
	v_mov_b32_e32 v96, 0
	s_cbranch_vccnz .LBB0_2540
	s_add_i32 s25, s19, s23
	s_addk_i32 s25, 0xfc5
	v_mad_i64_i32 v[78:79], vcc, s25, v94, v[48:49]
	v_add_co_u32_e32 v84, vcc, 0x2000, v78
	s_nop 1
	v_addc_co_u32_e32 v85, vcc, 0, v79, vcc
	global_load_dword v5, v[78:79], off nt
	global_load_dword v96, v[84:85], off offset:3072 nt
.LBB0_2540:
	s_andn2_b64 vcc, exec, s[28:29]
	v_mov_b32_e32 v98, 0
	v_mov_b32_e32 v101, 0
	v_mov_b32_e32 v100, 0
	s_cbranch_vccnz .LBB0_2542
	s_add_i32 s25, s19, s23
	s_add_i32 s28, s25, 0x1005
	v_mad_i64_i32 v[78:79], s[28:29], s28, v94, v[48:49]
	v_add_co_u32_e32 v84, vcc, 0x2000, v78
	s_addk_i32 s25, 0x1045
	s_nop 0
	v_addc_co_u32_e32 v85, vcc, 0, v79, vcc
	v_mad_i64_i32 v[88:89], s[28:29], s25, v94, v[48:49]
	v_add_co_u32_e32 v90, vcc, 0x2000, v88
	s_nop 1
	v_addc_co_u32_e32 v91, vcc, 0, v89, vcc
	global_load_dword v98, v[78:79], off nt
	global_load_dword v100, v[84:85], off offset:3072 nt
	global_load_dword v7, v[88:89], off nt
	global_load_dword v101, v[90:91], off offset:3072 nt
.LBB0_2542:
	s_or_b64 s[4:5], s[70:71], s[4:5]
	v_mov_b32_e32 v103, 0
	s_and_b64 vcc, exec, s[4:5]
	v_mov_b32_e32 v106, 0
	v_mov_b32_e32 v114, 0
	s_cbranch_vccnz .LBB0_2544
	s_add_i32 s4, s19, s23
	s_addk_i32 s4, 0x1085
	v_mad_i64_i32 v[78:79], s[4:5], s4, v94, v[48:49]
	v_add_co_u32_e32 v84, vcc, 0x2000, v78
	s_nop 1
	v_addc_co_u32_e32 v85, vcc, 0, v79, vcc
	global_load_dword v106, v[78:79], off nt
	global_load_dword v114, v[84:85], off offset:3072 nt
.LBB0_2544:
	s_cmp_gt_u32 s24, 62
	s_cselect_b64 s[4:5], -1, 0
	s_cmp_lt_u32 s24, 63
	s_cselect_b64 s[28:29], -1, 0
	s_or_b64 vcc, s[66:67], s[4:5]
	s_and_b64 vcc, exec, vcc
	v_mov_b32_e32 v123, 0
	s_cbranch_vccnz .LBB0_2546
	s_add_i32 s25, s19, s23
	s_addk_i32 s25, 0xfc6
	v_mad_i64_i32 v[78:79], vcc, s25, v94, v[48:49]
	v_add_co_u32_e32 v84, vcc, 0x2000, v78
	s_nop 1
	v_addc_co_u32_e32 v85, vcc, 0, v79, vcc
	global_load_dword v103, v[78:79], off nt
	global_load_dword v123, v[84:85], off offset:3072 nt
.LBB0_2546:
	v_mov_b32_e32 v124, 0
	s_andn2_b64 vcc, exec, s[28:29]
	v_mov_b32_e32 v129, 0
	v_mov_b32_e32 v128, 0
	v_mov_b32_e32 v133, 0
	v_mov_b32_e32 v131, 0
	s_cbranch_vccnz .LBB0_2548
	s_add_i32 s25, s19, s23
	s_add_i32 s28, s25, 0x1006
	v_mad_i64_i32 v[78:79], s[28:29], s28, v94, v[48:49]
	v_add_co_u32_e32 v84, vcc, 0x2000, v78
	s_addk_i32 s25, 0x1046
	s_nop 0
	v_addc_co_u32_e32 v85, vcc, 0, v79, vcc
	v_mad_i64_i32 v[88:89], s[28:29], s25, v94, v[48:49]
	v_add_co_u32_e32 v90, vcc, 0x2000, v88
	s_nop 1
	v_addc_co_u32_e32 v91, vcc, 0, v89, vcc
	global_load_dword v128, v[78:79], off nt
	global_load_dword v131, v[84:85], off offset:3072 nt
	global_load_dword v129, v[88:89], off nt
	global_load_dword v133, v[90:91], off offset:3072 nt
.LBB0_2548:
	s_or_b64 s[4:5], s[70:71], s[4:5]
	s_and_b64 vcc, exec, s[4:5]
	v_mov_b32_e32 v135, 0
	s_cbranch_vccnz .LBB0_2550
	s_add_i32 s4, s19, s23
	s_addk_i32 s4, 0x1086
	v_mad_i64_i32 v[78:79], s[4:5], s4, v94, v[48:49]
	v_add_co_u32_e32 v84, vcc, 0x2000, v78
	s_nop 1
	v_addc_co_u32_e32 v85, vcc, 0, v79, vcc
	global_load_dword v124, v[78:79], off nt
	global_load_dword v135, v[84:85], off offset:3072 nt
.LBB0_2550:
	s_cmp_gt_u32 s24, 61
	s_cselect_b64 s[4:5], -1, 0
	s_cmp_lt_u32 s24, 62
	s_cselect_b64 s[28:29], -1, 0
	s_or_b64 vcc, s[66:67], s[4:5]
	v_mov_b32_e32 v99, 0
	s_and_b64 vcc, exec, vcc
	v_mov_b32_e32 v2, 0
	v_mov_b32_e32 v97, 0
	s_cbranch_vccnz .LBB0_2552
	s_add_i32 s25, s19, s23
	s_addk_i32 s25, 0xfc7
	v_mad_i64_i32 v[78:79], vcc, s25, v94, v[48:49]
	v_add_co_u32_e32 v84, vcc, 0x2000, v78
	s_nop 1
	v_addc_co_u32_e32 v85, vcc, 0, v79, vcc
	global_load_dword v2, v[78:79], off nt
	global_load_dword v97, v[84:85], off offset:3072 nt
.LBB0_2552:
	s_andn2_b64 vcc, exec, s[28:29]
	v_mov_b32_e32 v112, 0
	v_mov_b32_e32 v115, 0
	v_mov_b32_e32 v113, 0
	s_cbranch_vccnz .LBB0_2554
	s_add_i32 s25, s19, s23
	s_add_i32 s28, s25, 0x1007
	v_mad_i64_i32 v[78:79], s[28:29], s28, v94, v[48:49]
	v_add_co_u32_e32 v84, vcc, 0x2000, v78
	s_addk_i32 s25, 0x1047
	s_nop 0
	v_addc_co_u32_e32 v85, vcc, 0, v79, vcc
	v_mad_i64_i32 v[88:89], s[28:29], s25, v94, v[48:49]
	v_add_co_u32_e32 v90, vcc, 0x2000, v88
	s_nop 1
	v_addc_co_u32_e32 v91, vcc, 0, v89, vcc
	global_load_dword v112, v[78:79], off nt
	global_load_dword v113, v[84:85], off offset:3072 nt
	global_load_dword v99, v[88:89], off nt
	global_load_dword v115, v[90:91], off offset:3072 nt
.LBB0_2554:
	s_or_b64 s[4:5], s[70:71], s[4:5]
	v_mov_b32_e32 v126, 0
	s_and_b64 vcc, exec, s[4:5]
	v_mov_b32_e32 v127, 0
	v_mov_b32_e32 v130, 0
	s_cbranch_vccnz .LBB0_2556
	s_add_i32 s4, s19, s23
	s_addk_i32 s4, 0x1087
	v_mad_i64_i32 v[78:79], s[4:5], s4, v94, v[48:49]
	v_add_co_u32_e32 v84, vcc, 0x2000, v78
	s_nop 1
	v_addc_co_u32_e32 v85, vcc, 0, v79, vcc
	global_load_dword v127, v[78:79], off nt
	global_load_dword v130, v[84:85], off offset:3072 nt
.LBB0_2556:
	s_cmp_gt_u32 s24, 60
	s_cselect_b64 s[4:5], -1, 0
	s_cmp_lt_u32 s24, 61
	s_cselect_b64 s[28:29], -1, 0
	s_or_b64 s[24:25], s[66:67], s[4:5]
	s_and_b64 vcc, exec, s[24:25]
	v_mov_b32_e32 v136, 0
	s_cbranch_vccnz .LBB0_2558
	s_add_i32 s24, s19, s23
	s_addk_i32 s24, 0xfc8
	v_mad_i64_i32 v[78:79], s[24:25], s24, v94, v[48:49]
	v_add_co_u32_e32 v84, vcc, 0x2000, v78
	s_nop 1
	v_addc_co_u32_e32 v85, vcc, 0, v79, vcc
	global_load_dword v126, v[78:79], off nt
	global_load_dword v136, v[84:85], off offset:3072 nt
.LBB0_2558:
	v_mov_b32_e32 v140, 0
	s_andn2_b64 vcc, exec, s[28:29]
	v_mov_b32_e32 v138, 0
	v_mov_b32_e32 v137, 0
	v_mov_b32_e32 v141, 0
	v_mov_b32_e32 v139, 0
	s_cbranch_vccnz .LBB0_2560
	s_add_i32 s28, s19, s23
	s_add_i32 s24, s28, 0x1008
	v_mad_i64_i32 v[78:79], s[24:25], s24, v94, v[48:49]
	v_add_co_u32_e32 v84, vcc, 0x2000, v78
	s_addk_i32 s28, 0x1048
	s_nop 0
	v_addc_co_u32_e32 v85, vcc, 0, v79, vcc
	v_mad_i64_i32 v[88:89], s[24:25], s28, v94, v[48:49]
	v_add_co_u32_e32 v90, vcc, 0x2000, v88
	s_nop 1
	v_addc_co_u32_e32 v91, vcc, 0, v89, vcc
	global_load_dword v137, v[78:79], off nt
	global_load_dword v139, v[84:85], off offset:3072 nt
	global_load_dword v138, v[88:89], off nt
	global_load_dword v141, v[90:91], off offset:3072 nt
.LBB0_2560:
	s_or_b64 s[4:5], s[70:71], s[4:5]
	s_and_b64 vcc, exec, s[4:5]
	v_mov_b32_e32 v142, 0
	s_cbranch_vccnz .LBB0_2536
	s_add_i32 s4, s19, s23
	s_addk_i32 s4, 0x1088
	v_mad_i64_i32 v[78:79], s[4:5], s4, v94, v[48:49]
	v_add_co_u32_e32 v84, vcc, 0x2000, v78
	s_nop 1
	v_addc_co_u32_e32 v85, vcc, 0, v79, vcc
	global_load_dword v142, v[78:79], off nt
	global_load_dword v140, v[84:85], off offset:3072 nt
	s_branch .LBB0_2536
